# P8 K-loop LDS-DMA loads in saddr form (SGPR base + VGPR offset), 16 v_lshl_add_u64 per iteration removed
# speedup vs baseline: 1.0037x; 1.0003x over previous
.Ldhs8_done:
	ds_read_b128 v[150:153], v147
	ds_read_b128 v[154:157], v147 offset:1024
	ds_read_b128 v[158:161], v147 offset:2048
	ds_read_b128 v[162:165], v147 offset:3072
	ds_read_b128 v[166:169], v148
	ds_read_b128 v[170:173], v148 offset:1024
	ds_read_b128 v[174:177], v148 offset:2048
	ds_read_b128 v[178:181], v148 offset:3072
	s_add_u32 s38, s36, 0xfffc0080
	s_addc_u32 s39, s37, -1
	s_cmp_eq_u32 s61, 12
	s_cselect_b32 s41, s27, s39
	s_cselect_b32 s40, s57, s38
	s_cselect_b32 s39, s25, s60
	s_cselect_b32 s38, s58, s59
	s_add_i32 m0, s35, 0xc000
	ds_read_b128 v[182:185], v149
	ds_read_b128 v[186:189], v149 offset:1024
	ds_read_b128 v[190:193], v149 offset:2048
	ds_read_b128 v[194:197], v149 offset:3072
	ds_read_b128 v[198:201], v149 offset:4096
	ds_read_b128 v[202:205], v149 offset:5120
	ds_read_b128 v[206:209], v149 offset:6144
	ds_read_b128 v[210:213], v149 offset:7168
	global_load_lds_dwordx4 v136, s[36:37]
	s_add_i32 m0, s35, 0xe000
	s_nop 0
	global_load_lds_dwordx4 v138, s[36:37]
	s_waitcnt vmcnt(9)
	s_waitcnt lgkmcnt(0)
	s_barrier
	s_setprio 1
	s_waitcnt lgkmcnt(0)
	v_mfma_f32_16x16x32_bf16 v[124:127], v[150:153], v[182:185], v[124:127]
	v_mfma_f32_16x16x32_bf16 v[120:123], v[158:161], v[182:185], v[120:123]
	v_mfma_f32_16x16x32_bf16 v[108:111], v[150:153], v[190:193], v[108:111]
	v_mfma_f32_16x16x32_bf16 v[104:107], v[158:161], v[190:193], v[104:107]
	v_mfma_f32_16x16x32_bf16 v[92:95], v[150:153], v[198:201], v[92:95]
	v_mfma_f32_16x16x32_bf16 v[88:91], v[158:161], v[198:201], v[88:91]
	v_mfma_f32_16x16x32_bf16 v[76:79], v[150:153], v[206:209], v[76:79]
	v_mfma_f32_16x16x32_bf16 v[72:75], v[158:161], v[206:209], v[72:75]
	v_mfma_f32_16x16x32_bf16 v[124:127], v[154:157], v[186:189], v[124:127]
	v_mfma_f32_16x16x32_bf16 v[120:123], v[162:165], v[186:189], v[120:123]
	v_mfma_f32_16x16x32_bf16 v[108:111], v[154:157], v[194:197], v[108:111]
	v_mfma_f32_16x16x32_bf16 v[104:107], v[162:165], v[194:197], v[104:107]
	v_mfma_f32_16x16x32_bf16 v[92:95], v[154:157], v[202:205], v[92:95]
	v_mfma_f32_16x16x32_bf16 v[88:91], v[162:165], v[202:205], v[88:91]
	v_mfma_f32_16x16x32_bf16 v[76:79], v[154:157], v[210:213], v[76:79]
	v_mfma_f32_16x16x32_bf16 v[72:75], v[162:165], v[210:213], v[72:75]
	s_setprio 0
	s_setprio 1
	v_mfma_f32_16x16x32_bf16 v[116:119], v[166:169], v[182:185], v[116:119]
	v_mfma_f32_16x16x32_bf16 v[112:115], v[174:177], v[182:185], v[112:115]
	v_mfma_f32_16x16x32_bf16 v[100:103], v[166:169], v[190:193], v[100:103]
	v_mfma_f32_16x16x32_bf16 v[96:99], v[174:177], v[190:193], v[96:99]
	v_mfma_f32_16x16x32_bf16 v[84:87], v[166:169], v[198:201], v[84:87]
	v_mfma_f32_16x16x32_bf16 v[80:83], v[174:177], v[198:201], v[80:83]
	v_mfma_f32_16x16x32_bf16 v[68:71], v[166:169], v[206:209], v[68:71]
	v_mfma_f32_16x16x32_bf16 v[64:67], v[174:177], v[206:209], v[64:67]
	v_mfma_f32_16x16x32_bf16 v[116:119], v[170:173], v[186:189], v[116:119]
	v_mfma_f32_16x16x32_bf16 v[112:115], v[178:181], v[186:189], v[112:115]
	v_mfma_f32_16x16x32_bf16 v[100:103], v[170:173], v[194:197], v[100:103]
	v_mfma_f32_16x16x32_bf16 v[96:99], v[178:181], v[194:197], v[96:99]
	v_mfma_f32_16x16x32_bf16 v[84:87], v[170:173], v[202:205], v[84:87]
	v_mfma_f32_16x16x32_bf16 v[80:83], v[178:181], v[202:205], v[80:83]
	v_mfma_f32_16x16x32_bf16 v[68:71], v[170:173], v[210:213], v[68:71]
	v_mfma_f32_16x16x32_bf16 v[64:67], v[178:181], v[210:213], v[64:67]
	s_setprio 0
	s_barrier
	s_add_i32 s62, s50, s3
	s_mov_b64 s[22:23], s[40:41]
	s_mov_b32 m0, s62
	ds_read_b128 v[182:185], v149 offset:16384
	ds_read_b128 v[186:189], v149 offset:17408
	ds_read_b128 v[190:193], v149 offset:18432
	ds_read_b128 v[194:197], v149 offset:19456
	ds_read_b128 v[198:201], v149 offset:20480
	ds_read_b128 v[202:205], v149 offset:21504
	ds_read_b128 v[206:209], v149 offset:22528
	ds_read_b128 v[210:213], v149 offset:23552
	global_load_lds_dwordx4 v130, s[38:39]
	s_add_i32 m0, s62, 0x2000
	s_add_u32 s62, s38, 0x40000
	s_addc_u32 s63, s39, 0
	s_add_i32 s64, s51, s3
	global_load_lds_dwordx4 v134, s[38:39]
	s_mov_b32 m0, s64
	s_nop 0
	global_load_lds_dwordx4 v130, s[62:63]
	s_add_i32 m0, s64, 0x2000
	s_nop 0
	global_load_lds_dwordx4 v134, s[62:63]
	s_mov_b32 m0, s35
	s_nop 0
	global_load_lds_dwordx4 v128, s[40:41]
	s_mov_b32 m0, s42
	s_nop 0
	global_load_lds_dwordx4 v132, s[40:41]
	s_waitcnt vmcnt(9)
	s_waitcnt lgkmcnt(0)
	s_barrier
	s_setprio 1
	s_waitcnt lgkmcnt(0)
	v_mfma_f32_16x16x32_bf16 v[60:63], v[150:153], v[182:185], v[60:63]
	v_mfma_f32_16x16x32_bf16 v[56:59], v[158:161], v[182:185], v[56:59]
	v_mfma_f32_16x16x32_bf16 v[44:47], v[150:153], v[190:193], v[44:47]
	v_mfma_f32_16x16x32_bf16 v[40:43], v[158:161], v[190:193], v[40:43]
	v_mfma_f32_16x16x32_bf16 v[28:31], v[150:153], v[198:201], v[28:31]
	v_mfma_f32_16x16x32_bf16 v[24:27], v[158:161], v[198:201], v[24:27]
	v_mfma_f32_16x16x32_bf16 v[12:15], v[150:153], v[206:209], v[12:15]
	v_mfma_f32_16x16x32_bf16 v[8:11], v[158:161], v[206:209], v[8:11]
	v_mfma_f32_16x16x32_bf16 v[60:63], v[154:157], v[186:189], v[60:63]
	v_mfma_f32_16x16x32_bf16 v[56:59], v[162:165], v[186:189], v[56:59]
	v_mfma_f32_16x16x32_bf16 v[44:47], v[154:157], v[194:197], v[44:47]
	v_mfma_f32_16x16x32_bf16 v[40:43], v[162:165], v[194:197], v[40:43]
	v_mfma_f32_16x16x32_bf16 v[28:31], v[154:157], v[202:205], v[28:31]
	v_mfma_f32_16x16x32_bf16 v[24:27], v[162:165], v[202:205], v[24:27]
	v_mfma_f32_16x16x32_bf16 v[12:15], v[154:157], v[210:213], v[12:15]
	v_mfma_f32_16x16x32_bf16 v[8:11], v[162:165], v[210:213], v[8:11]
	s_setprio 0
	s_setprio 1
	v_mfma_f32_16x16x32_bf16 v[52:55], v[166:169], v[182:185], v[52:55]
	v_mfma_f32_16x16x32_bf16 v[48:51], v[174:177], v[182:185], v[48:51]
	v_mfma_f32_16x16x32_bf16 v[36:39], v[166:169], v[190:193], v[36:39]
	v_mfma_f32_16x16x32_bf16 v[32:35], v[174:177], v[190:193], v[32:35]
	v_mfma_f32_16x16x32_bf16 v[20:23], v[166:169], v[198:201], v[20:23]
	v_mfma_f32_16x16x32_bf16 v[16:19], v[174:177], v[198:201], v[16:19]
	v_mfma_f32_16x16x32_bf16 v[4:7], v[166:169], v[206:209], v[4:7]
	v_mfma_f32_16x16x32_bf16 v[0:3], v[174:177], v[206:209], v[0:3]
	v_mfma_f32_16x16x32_bf16 v[52:55], v[170:173], v[186:189], v[52:55]
	v_mfma_f32_16x16x32_bf16 v[48:51], v[178:181], v[186:189], v[48:51]
	v_mfma_f32_16x16x32_bf16 v[36:39], v[170:173], v[194:197], v[36:39]
	v_mfma_f32_16x16x32_bf16 v[32:35], v[178:181], v[194:197], v[32:35]
	v_mfma_f32_16x16x32_bf16 v[20:23], v[170:173], v[202:205], v[20:23]
	v_mfma_f32_16x16x32_bf16 v[16:19], v[178:181], v[202:205], v[16:19]
	v_mfma_f32_16x16x32_bf16 v[4:7], v[170:173], v[210:213], v[4:7]
	v_mfma_f32_16x16x32_bf16 v[0:3], v[178:181], v[210:213], v[0:3]
	s_setprio 0
	s_barrier
	s_add_i32 s62, 0, 0x18000
	s_add_i32 s63, 0, 0x1c000
	v_add_u32_e32 v162, s62, v145
	v_add_u32_e32 v178, s63, v145
	ds_read_b128 v[150:153], v162
	ds_read_b128 v[154:157], v162 offset:1024
	ds_read_b128 v[158:161], v162 offset:2048
	ds_read_b128 v[162:165], v162 offset:3072
	ds_read_b128 v[166:169], v178
	ds_read_b128 v[170:173], v178 offset:1024
	ds_read_b128 v[174:177], v178 offset:2048
	ds_read_b128 v[178:181], v178 offset:3072
	s_add_u32 s40, s40, 0x40000
	s_addc_u32 s41, s41, 0
	s_mov_b32 m0, s43
	s_nop 0
	ds_read_b128 v[182:185], v149 offset:32768
	ds_read_b128 v[186:189], v149 offset:33792
	ds_read_b128 v[190:193], v149 offset:34816
	ds_read_b128 v[194:197], v149 offset:35840
	ds_read_b128 v[198:201], v149 offset:36864
	ds_read_b128 v[202:205], v149 offset:37888
	ds_read_b128 v[206:209], v149 offset:38912
	ds_read_b128 v[210:213], v149 offset:39936
	global_load_lds_dwordx4 v128, s[40:41]
	s_mov_b32 m0, s44
	s_nop 0
	global_load_lds_dwordx4 v132, s[40:41]
	s_waitcnt vmcnt(8)
	s_waitcnt lgkmcnt(0)
	s_barrier
	s_setprio 1
	s_waitcnt lgkmcnt(0)
	v_mfma_f32_16x16x32_bf16 v[124:127], v[150:153], v[182:185], v[124:127]
	v_mfma_f32_16x16x32_bf16 v[120:123], v[158:161], v[182:185], v[120:123]
	v_mfma_f32_16x16x32_bf16 v[108:111], v[150:153], v[190:193], v[108:111]
	v_mfma_f32_16x16x32_bf16 v[104:107], v[158:161], v[190:193], v[104:107]
	v_mfma_f32_16x16x32_bf16 v[92:95], v[150:153], v[198:201], v[92:95]
	v_mfma_f32_16x16x32_bf16 v[88:91], v[158:161], v[198:201], v[88:91]
	v_mfma_f32_16x16x32_bf16 v[76:79], v[150:153], v[206:209], v[76:79]
	v_mfma_f32_16x16x32_bf16 v[72:75], v[158:161], v[206:209], v[72:75]
	v_mfma_f32_16x16x32_bf16 v[124:127], v[154:157], v[186:189], v[124:127]
	v_mfma_f32_16x16x32_bf16 v[120:123], v[162:165], v[186:189], v[120:123]
	v_mfma_f32_16x16x32_bf16 v[108:111], v[154:157], v[194:197], v[108:111]
	v_mfma_f32_16x16x32_bf16 v[104:107], v[162:165], v[194:197], v[104:107]
	v_mfma_f32_16x16x32_bf16 v[92:95], v[154:157], v[202:205], v[92:95]
	v_mfma_f32_16x16x32_bf16 v[88:91], v[162:165], v[202:205], v[88:91]
	v_mfma_f32_16x16x32_bf16 v[76:79], v[154:157], v[210:213], v[76:79]
	v_mfma_f32_16x16x32_bf16 v[72:75], v[162:165], v[210:213], v[72:75]
	s_setprio 0
	s_setprio 1
	v_mfma_f32_16x16x32_bf16 v[116:119], v[166:169], v[182:185], v[116:119]
	v_mfma_f32_16x16x32_bf16 v[112:115], v[174:177], v[182:185], v[112:115]
	v_mfma_f32_16x16x32_bf16 v[100:103], v[166:169], v[190:193], v[100:103]
	v_mfma_f32_16x16x32_bf16 v[96:99], v[174:177], v[190:193], v[96:99]
	v_mfma_f32_16x16x32_bf16 v[84:87], v[166:169], v[198:201], v[84:87]
	v_mfma_f32_16x16x32_bf16 v[80:83], v[174:177], v[198:201], v[80:83]
	v_mfma_f32_16x16x32_bf16 v[68:71], v[166:169], v[206:209], v[68:71]
	v_mfma_f32_16x16x32_bf16 v[64:67], v[174:177], v[206:209], v[64:67]
	v_mfma_f32_16x16x32_bf16 v[116:119], v[170:173], v[186:189], v[116:119]
	v_mfma_f32_16x16x32_bf16 v[112:115], v[178:181], v[186:189], v[112:115]
	v_mfma_f32_16x16x32_bf16 v[100:103], v[170:173], v[194:197], v[100:103]
	v_mfma_f32_16x16x32_bf16 v[96:99], v[178:181], v[194:197], v[96:99]
	v_mfma_f32_16x16x32_bf16 v[84:87], v[170:173], v[202:205], v[84:87]
	v_mfma_f32_16x16x32_bf16 v[80:83], v[178:181], v[202:205], v[80:83]
	v_mfma_f32_16x16x32_bf16 v[68:71], v[170:173], v[210:213], v[68:71]
	v_mfma_f32_16x16x32_bf16 v[64:67], v[178:181], v[210:213], v[64:67]
	s_setprio 0
	s_barrier
	s_add_i32 s40, s62, s3
	s_add_i32 m0, s40, 0xffffff80
	s_nop 0
	ds_read_b128 v[182:185], v149 offset:49152
	ds_read_b128 v[186:189], v149 offset:50176
	ds_read_b128 v[190:193], v149 offset:51200
	ds_read_b128 v[194:197], v149 offset:52224
	ds_read_b128 v[198:201], v149 offset:53248
	ds_read_b128 v[202:205], v149 offset:54272
	ds_read_b128 v[206:209], v149 offset:55296
	ds_read_b128 v[210:213], v149 offset:56320
	global_load_lds_dwordx4 v130, s[38:39] offset:128
	s_add_i32 m0, s40, 0x1f80
	s_add_i32 s40, s63, s3
	global_load_lds_dwordx4 v134, s[38:39] offset:128
	s_add_u32 s38, s38, 0x40080
	s_addc_u32 s39, s39, 0
	s_mov_b32 m0, s40
	s_nop 0
	global_load_lds_dwordx4 v130, s[38:39]
	s_add_i32 m0, s40, 0x2000
	s_nop 0
	global_load_lds_dwordx4 v134, s[38:39]
	s_add_i32 m0, s47, 0xffffff80
	s_nop 0
	global_load_lds_dwordx4 v128, s[22:23] offset:128
	s_add_i32 m0, s48, 0xffffff80
	s_nop 0
	global_load_lds_dwordx4 v132, s[22:23] offset:128
	s_waitcnt vmcnt(8)
	s_waitcnt lgkmcnt(0)
	s_barrier
	s_setprio 1
	s_waitcnt lgkmcnt(0)
	v_mfma_f32_16x16x32_bf16 v[60:63], v[150:153], v[182:185], v[60:63]
	v_mfma_f32_16x16x32_bf16 v[56:59], v[158:161], v[182:185], v[56:59]
	v_mfma_f32_16x16x32_bf16 v[44:47], v[150:153], v[190:193], v[44:47]
	v_mfma_f32_16x16x32_bf16 v[40:43], v[158:161], v[190:193], v[40:43]
	v_mfma_f32_16x16x32_bf16 v[28:31], v[150:153], v[198:201], v[28:31]
	v_mfma_f32_16x16x32_bf16 v[24:27], v[158:161], v[198:201], v[24:27]
	v_mfma_f32_16x16x32_bf16 v[12:15], v[150:153], v[206:209], v[12:15]
	v_mfma_f32_16x16x32_bf16 v[8:11], v[158:161], v[206:209], v[8:11]
	v_mfma_f32_16x16x32_bf16 v[60:63], v[154:157], v[186:189], v[60:63]
	v_mfma_f32_16x16x32_bf16 v[56:59], v[162:165], v[186:189], v[56:59]
	v_mfma_f32_16x16x32_bf16 v[44:47], v[154:157], v[194:197], v[44:47]
	v_mfma_f32_16x16x32_bf16 v[40:43], v[162:165], v[194:197], v[40:43]
	v_mfma_f32_16x16x32_bf16 v[28:31], v[154:157], v[202:205], v[28:31]
	v_mfma_f32_16x16x32_bf16 v[24:27], v[162:165], v[202:205], v[24:27]
	v_mfma_f32_16x16x32_bf16 v[12:15], v[154:157], v[210:213], v[12:15]
	v_mfma_f32_16x16x32_bf16 v[8:11], v[162:165], v[210:213], v[8:11]
	s_setprio 0
	s_setprio 1
	v_mfma_f32_16x16x32_bf16 v[52:55], v[166:169], v[182:185], v[52:55]
	v_mfma_f32_16x16x32_bf16 v[48:51], v[174:177], v[182:185], v[48:51]
	v_mfma_f32_16x16x32_bf16 v[36:39], v[166:169], v[190:193], v[36:39]
	v_mfma_f32_16x16x32_bf16 v[32:35], v[174:177], v[190:193], v[32:35]
	v_mfma_f32_16x16x32_bf16 v[20:23], v[166:169], v[198:201], v[20:23]
	v_mfma_f32_16x16x32_bf16 v[16:19], v[174:177], v[198:201], v[16:19]
	v_mfma_f32_16x16x32_bf16 v[4:7], v[166:169], v[206:209], v[4:7]
	v_mfma_f32_16x16x32_bf16 v[0:3], v[174:177], v[206:209], v[0:3]
	v_mfma_f32_16x16x32_bf16 v[52:55], v[170:173], v[186:189], v[52:55]
	v_mfma_f32_16x16x32_bf16 v[48:51], v[178:181], v[186:189], v[48:51]
	v_mfma_f32_16x16x32_bf16 v[36:39], v[170:173], v[194:197], v[36:39]
	v_mfma_f32_16x16x32_bf16 v[32:35], v[178:181], v[194:197], v[32:35]
	v_mfma_f32_16x16x32_bf16 v[20:23], v[170:173], v[202:205], v[20:23]
	v_mfma_f32_16x16x32_bf16 v[16:19], v[178:181], v[202:205], v[16:19]
	v_mfma_f32_16x16x32_bf16 v[4:7], v[170:173], v[210:213], v[4:7]
	v_mfma_f32_16x16x32_bf16 v[0:3], v[178:181], v[210:213], v[0:3]
	s_setprio 0
	s_barrier
	s_add_i32 s61, s61, 2
	s_add_u32 s36, s36, 0x100
	s_addc_u32 s37, s37, 0
	s_add_u32 s59, s59, 0x100
	s_addc_u32 s60, s60, 0
	s_cmp_gt_u32 s61, 13
	s_cbranch_scc0 .LBB0_877
	s_and_b64 vcc, exec, s[14:15]
	s_cbranch_vccz .LBB0_880
	s_barrier
